# grid barrier: workgroups watch the cross-XCD generation word directly; L1/L2 invalidate issued at arrival (XCD last arriver: with its L2 writeback, before arriving cross-XCD) instead of after the rele
# speedup vs baseline: 1.0224x; 1.0172x over previous
; __device__ __forceinline__ unsigned xb_ld(unsigned* p)              { return __hip_atomic_load(p, __ATOMIC_RELAXED, __HIP_MEMORY_SCOPE_AGENT); }
; __device__ __forceinline__ unsigned xb_add(unsigned* p, unsigned v) { return __hip_atomic_fetch_add(p, v, __ATOMIC_RELAXED, __HIP_MEMORY_SCOPE_AGENT); }
; #define XB_SPIN(cond, bar) do { unsigned _sp = 0; while (cond) { __builtin_amdgcn_s_sleep(1); \
;     if ((++_sp & 255u) == 0u) { if (xb_ld(&(bar)[XB_TMO])) break; if (_sp > XB_SPIN_CAP) { atomicAdd(&(bar)[XB_TMO], 1u); break; } } } } while (0)
; __device__ __forceinline__ void xcd_barrier(const XcdBarrier& b) {
;     ...
;         const unsigned old = xb_add(&bar[XB_XSUB(b.x)], 1u);
;         const unsigned gen = old / nloc;
;         if (old + 1u == (gen + 1u) * nloc) {
;             __builtin_amdgcn_fence(__ATOMIC_RELEASE, "agent");
;             asm volatile("s_waitcnt vmcnt(0)" ::: "memory");
;             const unsigned og = xb_add(&bar[XB_TOP], 1u);
;             const unsigned tg = og / nx;
;             if (og + 1u == (tg + 1u) * nx) xb_add(&bar[XB_TOPGEN], 1u);
;             else XB_SPIN(xb_ld(&bar[XB_TOPGEN]) == tg, bar);
;             __builtin_amdgcn_fence(__ATOMIC_ACQUIRE, "agent");
;             xb_add(&bar[XB_XGEN(b.x)], 1u);
;             asm volatile("s_waitcnt vmcnt(0)" ::: "memory");
;         } else {
;             XB_SPIN(xb_ld(&bar[XB_XGEN(b.x)]) == gen, bar);
;             __builtin_amdgcn_fence(__ATOMIC_ACQUIRE, "agent");
.LBB0_70:
	s_or_b64 exec, exec, s[10:11]
	v_cvt_f32_u32_e32 v4, v2
	s_waitcnt vmcnt(0)
	v_readfirstlane_b32 s0, v3
	v_sub_u32_e32 v3, 0, v2
	v_rcp_iflag_f32_e32 v4, v4
	v_add_u32_e32 v5, s0, v1
	v_mul_f32_e32 v4, 0x4f7ffffe, v4
	v_cvt_u32_f32_e32 v4, v4
	v_mul_lo_u32 v1, v3, v4
	v_mul_hi_u32 v1, v4, v1
	v_add_u32_e32 v1, v4, v1
	v_mul_hi_u32 v1, v5, v1
	v_mul_lo_u32 v3, v1, v2
	v_sub_u32_e32 v3, v5, v3
	v_add_u32_e32 v4, 1, v1
	v_cmp_ge_u32_e32 vcc, v3, v2
	s_nop 1
	v_cndmask_b32_e32 v1, v1, v4, vcc
	v_sub_u32_e32 v4, v3, v2
	v_cndmask_b32_e32 v3, v3, v4, vcc
	v_add_u32_e32 v4, 1, v1
	v_cmp_ge_u32_e32 vcc, v3, v2
	v_add_u32_e32 v3, 1, v5
	s_nop 0
	v_cndmask_b32_e32 v1, v1, v4, vcc
	v_mul_lo_u32 v4, v2, v1
	v_add_u32_e32 v2, v4, v2
	v_cmp_ne_u32_e32 vcc, v3, v2
	s_and_saveexec_b64 s[0:1], vcc
	s_xor_b64 s[10:11], exec, s[0:1]
	s_cbranch_execz .LBB0_84
	s_waitcnt lgkmcnt(0)
	buffer_inv sc1
	v_mov_b32_e32 v0, 0x3500
	global_load_dword v0, v0, s[86:87] sc1
	s_add_u32 s14, s86, 0x3500
	s_addc_u32 s15, s87, 0
	s_waitcnt vmcnt(0)
	v_cmp_eq_u32_e32 vcc, v0, v1
	s_and_saveexec_b64 s[12:13], vcc
	s_cbranch_execz .LBB0_83
	s_mov_b32 s3, 1
	s_mov_b64 s[16:17], 0
	v_mov_b32_e32 v0, 0
	s_branch .LBB0_74

; __device__ __forceinline__ unsigned xb_ld(unsigned* p)              { return __hip_atomic_load(p, __ATOMIC_RELAXED, __HIP_MEMORY_SCOPE_AGENT); }
; __device__ __forceinline__ unsigned xb_add(unsigned* p, unsigned v) { return __hip_atomic_fetch_add(p, v, __ATOMIC_RELAXED, __HIP_MEMORY_SCOPE_AGENT); }
; #define XB_SPIN(cond, bar) do { unsigned _sp = 0; while (cond) { __builtin_amdgcn_s_sleep(1); \
;     if ((++_sp & 255u) == 0u) { if (xb_ld(&(bar)[XB_TMO])) break; if (_sp > XB_SPIN_CAP) { atomicAdd(&(bar)[XB_TMO], 1u); break; } } } } while (0)
; __device__ __forceinline__ void xcd_barrier(const XcdBarrier& b) {
;     ...
;         if (old + 1u == (gen + 1u) * nloc) {
;             __builtin_amdgcn_fence(__ATOMIC_RELEASE, "agent");
;             asm volatile("s_waitcnt vmcnt(0)" ::: "memory");
;             const unsigned og = xb_add(&bar[XB_TOP], 1u);
;             const unsigned tg = og / nx;
;             if (og + 1u == (tg + 1u) * nx) xb_add(&bar[XB_TOPGEN], 1u);
;             else XB_SPIN(xb_ld(&bar[XB_TOPGEN]) == tg, bar);
;             __builtin_amdgcn_fence(__ATOMIC_ACQUIRE, "agent");
;             xb_add(&bar[XB_XGEN(b.x)], 1u);
;             asm volatile("s_waitcnt vmcnt(0)" ::: "memory");
;         } else {
;             XB_SPIN(xb_ld(&bar[XB_XGEN(b.x)]) == gen, bar);
;             __builtin_amdgcn_fence(__ATOMIC_ACQUIRE, "agent");
;             asm volatile("s_waitcnt vmcnt(0)" ::: "memory");
;         }
.LBB0_83:
	s_or_b64 exec, exec, s[12:13]
	s_waitcnt vmcnt(0)
	s_waitcnt vmcnt(0)
.LBB0_84:
	s_andn2_saveexec_b64 s[0:1], s[10:11]
	s_cbranch_execz .LBB0_104
	s_mov_b64 s[0:1], exec
	buffer_wbl2 sc1
	buffer_inv sc1
	s_waitcnt lgkmcnt(0)
	s_waitcnt vmcnt(0)
	v_mbcnt_lo_u32_b32 v1, s0, 0
	v_mbcnt_hi_u32_b32 v1, s1, v1
	v_cmp_eq_u32_e32 vcc, 0, v1
	s_and_saveexec_b64 s[10:11], vcc
	s_cbranch_execz .LBB0_87
	s_bcnt1_i32_b64 s0, s[0:1]
	v_mov_b32_e32 v2, 0x3000
	v_mov_b32_e32 v3, s0
	global_atomic_add v2, v2, v3, s[86:87] offset:1024 sc0

; __device__ __forceinline__ unsigned xb_ld(unsigned* p)              { return __hip_atomic_load(p, __ATOMIC_RELAXED, __HIP_MEMORY_SCOPE_AGENT); }
; __device__ __forceinline__ unsigned xb_add(unsigned* p, unsigned v) { return __hip_atomic_fetch_add(p, v, __ATOMIC_RELAXED, __HIP_MEMORY_SCOPE_AGENT); }
; #define XB_SPIN(cond, bar) do { unsigned _sp = 0; while (cond) { __builtin_amdgcn_s_sleep(1); \
;     if ((++_sp & 255u) == 0u) { if (xb_ld(&(bar)[XB_TMO])) break; if (_sp > XB_SPIN_CAP) { atomicAdd(&(bar)[XB_TMO], 1u); break; } } } } while (0)
; __device__ __forceinline__ void xcd_barrier(const XcdBarrier& b) {
;     ...
;             const unsigned og = xb_add(&bar[XB_TOP], 1u);
;             const unsigned tg = og / nx;
;             if (og + 1u == (tg + 1u) * nx) xb_add(&bar[XB_TOPGEN], 1u);
;             else XB_SPIN(xb_ld(&bar[XB_TOPGEN]) == tg, bar);
;             __builtin_amdgcn_fence(__ATOMIC_ACQUIRE, "agent");
;             xb_add(&bar[XB_XGEN(b.x)], 1u);
;             asm volatile("s_waitcnt vmcnt(0)" ::: "memory");
.LBB0_101:
	s_or_b64 exec, exec, s[10:11]
	s_mov_b64 s[0:1], exec
	v_mbcnt_lo_u32_b32 v0, s0, 0
	v_mbcnt_hi_u32_b32 v0, s1, v0
	v_cmp_eq_u32_e32 vcc, 0, v0
	s_waitcnt vmcnt(0)
	s_and_saveexec_b64 s[10:11], vcc
	s_cbranch_execz .LBB0_103
	s_bcnt1_i32_b64 s0, s[0:1]
	v_mov_b32_e32 v0, 0x2000
	v_mov_b32_e32 v1, s0

; __device__ __forceinline__ unsigned xb_ld(unsigned* p)              { return __hip_atomic_load(p, __ATOMIC_RELAXED, __HIP_MEMORY_SCOPE_AGENT); }
; __device__ __forceinline__ unsigned xb_add(unsigned* p, unsigned v) { return __hip_atomic_fetch_add(p, v, __ATOMIC_RELAXED, __HIP_MEMORY_SCOPE_AGENT); }
; #define XB_SPIN(cond, bar) do { unsigned _sp = 0; while (cond) { __builtin_amdgcn_s_sleep(1); \
;     if ((++_sp & 255u) == 0u) { if (xb_ld(&(bar)[XB_TMO])) break; if (_sp > XB_SPIN_CAP) { atomicAdd(&(bar)[XB_TMO], 1u); break; } } } } while (0)
; __device__ __forceinline__ void xcd_barrier(const XcdBarrier& b) {
;     ...
;         const unsigned old = xb_add(&bar[XB_XSUB(b.x)], 1u);
;         const unsigned gen = old / nloc;
;         if (old + 1u == (gen + 1u) * nloc) {
;             __builtin_amdgcn_fence(__ATOMIC_RELEASE, "agent");
;             asm volatile("s_waitcnt vmcnt(0)" ::: "memory");
;             const unsigned og = xb_add(&bar[XB_TOP], 1u);
;             const unsigned tg = og / nx;
;             if (og + 1u == (tg + 1u) * nx) xb_add(&bar[XB_TOPGEN], 1u);
;             else XB_SPIN(xb_ld(&bar[XB_TOPGEN]) == tg, bar);
;             __builtin_amdgcn_fence(__ATOMIC_ACQUIRE, "agent");
;             xb_add(&bar[XB_XGEN(b.x)], 1u);
;             asm volatile("s_waitcnt vmcnt(0)" ::: "memory");
;         } else {
;             XB_SPIN(xb_ld(&bar[XB_XGEN(b.x)]) == gen, bar);
;             __builtin_amdgcn_fence(__ATOMIC_ACQUIRE, "agent");
.LBB0_1811:
	s_or_b64 exec, exec, s[8:9]
	v_cvt_f32_u32_e32 v4, v2
	s_waitcnt vmcnt(0)
	v_readfirstlane_b32 s0, v3
	v_sub_u32_e32 v3, 0, v2
	v_rcp_iflag_f32_e32 v4, v4
	v_add_u32_e32 v5, s0, v1
	v_mul_f32_e32 v4, 0x4f7ffffe, v4
	v_cvt_u32_f32_e32 v4, v4
	v_mul_lo_u32 v1, v3, v4
	v_mul_hi_u32 v1, v4, v1
	v_add_u32_e32 v1, v4, v1
	v_mul_hi_u32 v1, v5, v1
	v_mul_lo_u32 v3, v1, v2
	v_sub_u32_e32 v3, v5, v3
	v_add_u32_e32 v4, 1, v1
	v_cmp_ge_u32_e32 vcc, v3, v2
	s_nop 1
	v_cndmask_b32_e32 v1, v1, v4, vcc
	v_sub_u32_e32 v4, v3, v2
	v_cndmask_b32_e32 v3, v3, v4, vcc
	v_add_u32_e32 v4, 1, v1
	v_cmp_ge_u32_e32 vcc, v3, v2
	v_add_u32_e32 v3, 1, v5
	s_nop 0
	v_cndmask_b32_e32 v1, v1, v4, vcc
	v_mul_lo_u32 v4, v2, v1
	v_add_u32_e32 v2, v4, v2
	v_cmp_ne_u32_e32 vcc, v3, v2
	s_and_saveexec_b64 s[0:1], vcc
	s_xor_b64 s[8:9], exec, s[0:1]
	s_cbranch_execz .LBB0_1825
	s_waitcnt lgkmcnt(0)
	buffer_inv sc1
	v_mov_b32_e32 v0, 0x3500
	global_load_dword v0, v0, s[86:87] sc1
	s_add_u32 s12, s86, 0x3500
	s_addc_u32 s13, s87, 0
	s_waitcnt vmcnt(0)
	v_cmp_eq_u32_e32 vcc, v0, v1
	s_and_saveexec_b64 s[10:11], vcc
	s_cbranch_execz .LBB0_1824
	s_mov_b32 s3, 1
	s_mov_b64 s[14:15], 0
	v_mov_b32_e32 v0, 0
	s_branch .LBB0_1815

; __device__ __forceinline__ unsigned xb_ld(unsigned* p)              { return __hip_atomic_load(p, __ATOMIC_RELAXED, __HIP_MEMORY_SCOPE_AGENT); }
; __device__ __forceinline__ unsigned xb_add(unsigned* p, unsigned v) { return __hip_atomic_fetch_add(p, v, __ATOMIC_RELAXED, __HIP_MEMORY_SCOPE_AGENT); }
; #define XB_SPIN(cond, bar) do { unsigned _sp = 0; while (cond) { __builtin_amdgcn_s_sleep(1); \
;     if ((++_sp & 255u) == 0u) { if (xb_ld(&(bar)[XB_TMO])) break; if (_sp > XB_SPIN_CAP) { atomicAdd(&(bar)[XB_TMO], 1u); break; } } } } while (0)
; __device__ __forceinline__ void xcd_barrier(const XcdBarrier& b) {
;     ...
;         if (old + 1u == (gen + 1u) * nloc) {
;             __builtin_amdgcn_fence(__ATOMIC_RELEASE, "agent");
;             asm volatile("s_waitcnt vmcnt(0)" ::: "memory");
;             const unsigned og = xb_add(&bar[XB_TOP], 1u);
;             const unsigned tg = og / nx;
;             if (og + 1u == (tg + 1u) * nx) xb_add(&bar[XB_TOPGEN], 1u);
;             else XB_SPIN(xb_ld(&bar[XB_TOPGEN]) == tg, bar);
;             __builtin_amdgcn_fence(__ATOMIC_ACQUIRE, "agent");
;             xb_add(&bar[XB_XGEN(b.x)], 1u);
;             asm volatile("s_waitcnt vmcnt(0)" ::: "memory");
;         } else {
;             XB_SPIN(xb_ld(&bar[XB_XGEN(b.x)]) == gen, bar);
;             __builtin_amdgcn_fence(__ATOMIC_ACQUIRE, "agent");
;             asm volatile("s_waitcnt vmcnt(0)" ::: "memory");
;         }
.LBB0_1824:
	s_or_b64 exec, exec, s[10:11]
	s_waitcnt vmcnt(0)
	s_waitcnt vmcnt(0)
.LBB0_1825:
	s_andn2_saveexec_b64 s[0:1], s[8:9]
	s_cbranch_execz .LBB0_1845
	s_mov_b64 s[0:1], exec
	buffer_wbl2 sc1
	buffer_inv sc1
	s_waitcnt lgkmcnt(0)
	s_waitcnt vmcnt(0)
	v_mbcnt_lo_u32_b32 v1, s0, 0
	v_mbcnt_hi_u32_b32 v1, s1, v1
	v_cmp_eq_u32_e32 vcc, 0, v1
	s_and_saveexec_b64 s[8:9], vcc
	s_cbranch_execz .LBB0_1828
	s_bcnt1_i32_b64 s0, s[0:1]
	v_mov_b32_e32 v2, 0x3000
	v_mov_b32_e32 v3, s0
	global_atomic_add v2, v2, v3, s[86:87] offset:1024 sc0

; __device__ __forceinline__ unsigned xb_ld(unsigned* p)              { return __hip_atomic_load(p, __ATOMIC_RELAXED, __HIP_MEMORY_SCOPE_AGENT); }
; __device__ __forceinline__ unsigned xb_add(unsigned* p, unsigned v) { return __hip_atomic_fetch_add(p, v, __ATOMIC_RELAXED, __HIP_MEMORY_SCOPE_AGENT); }
; #define XB_SPIN(cond, bar) do { unsigned _sp = 0; while (cond) { __builtin_amdgcn_s_sleep(1); \
;     if ((++_sp & 255u) == 0u) { if (xb_ld(&(bar)[XB_TMO])) break; if (_sp > XB_SPIN_CAP) { atomicAdd(&(bar)[XB_TMO], 1u); break; } } } } while (0)
; __device__ __forceinline__ void xcd_barrier(const XcdBarrier& b) {
;     ...
;             const unsigned og = xb_add(&bar[XB_TOP], 1u);
;             const unsigned tg = og / nx;
;             if (og + 1u == (tg + 1u) * nx) xb_add(&bar[XB_TOPGEN], 1u);
;             else XB_SPIN(xb_ld(&bar[XB_TOPGEN]) == tg, bar);
;             __builtin_amdgcn_fence(__ATOMIC_ACQUIRE, "agent");
;             xb_add(&bar[XB_XGEN(b.x)], 1u);
;             asm volatile("s_waitcnt vmcnt(0)" ::: "memory");
.LBB0_1842:
	s_or_b64 exec, exec, s[8:9]
	s_mov_b64 s[0:1], exec
	v_mbcnt_lo_u32_b32 v0, s0, 0
	v_mbcnt_hi_u32_b32 v0, s1, v0
	v_cmp_eq_u32_e32 vcc, 0, v0
	s_waitcnt vmcnt(0)
	s_and_saveexec_b64 s[8:9], vcc
	s_cbranch_execz .LBB0_1844
	s_bcnt1_i32_b64 s0, s[0:1]
	v_mov_b32_e32 v0, 0x2000
	v_mov_b32_e32 v1, s0

; __device__ __forceinline__ unsigned xb_ld(unsigned* p)              { return __hip_atomic_load(p, __ATOMIC_RELAXED, __HIP_MEMORY_SCOPE_AGENT); }
; __device__ __forceinline__ unsigned xb_add(unsigned* p, unsigned v) { return __hip_atomic_fetch_add(p, v, __ATOMIC_RELAXED, __HIP_MEMORY_SCOPE_AGENT); }
; #define XB_SPIN(cond, bar) do { unsigned _sp = 0; while (cond) { __builtin_amdgcn_s_sleep(1); \
;     if ((++_sp & 255u) == 0u) { if (xb_ld(&(bar)[XB_TMO])) break; if (_sp > XB_SPIN_CAP) { atomicAdd(&(bar)[XB_TMO], 1u); break; } } } } while (0)
; __device__ __forceinline__ void xcd_barrier(const XcdBarrier& b) {
;     ...
;         const unsigned old = xb_add(&bar[XB_XSUB(b.x)], 1u);
;         const unsigned gen = old / nloc;
;         if (old + 1u == (gen + 1u) * nloc) {
;             __builtin_amdgcn_fence(__ATOMIC_RELEASE, "agent");
;             asm volatile("s_waitcnt vmcnt(0)" ::: "memory");
;             const unsigned og = xb_add(&bar[XB_TOP], 1u);
;             const unsigned tg = og / nx;
;             if (og + 1u == (tg + 1u) * nx) xb_add(&bar[XB_TOPGEN], 1u);
;             else XB_SPIN(xb_ld(&bar[XB_TOPGEN]) == tg, bar);
;             __builtin_amdgcn_fence(__ATOMIC_ACQUIRE, "agent");
;             xb_add(&bar[XB_XGEN(b.x)], 1u);
;             asm volatile("s_waitcnt vmcnt(0)" ::: "memory");
;         } else {
;             XB_SPIN(xb_ld(&bar[XB_XGEN(b.x)]) == gen, bar);
;             __builtin_amdgcn_fence(__ATOMIC_ACQUIRE, "agent");
.LBB0_1936:
	s_or_b64 exec, exec, s[8:9]
	v_cvt_f32_u32_e32 v4, v2
	s_waitcnt vmcnt(0)
	v_readfirstlane_b32 s0, v3
	v_sub_u32_e32 v3, 0, v2
	v_rcp_iflag_f32_e32 v4, v4
	v_add_u32_e32 v5, s0, v1
	v_mul_f32_e32 v4, 0x4f7ffffe, v4
	v_cvt_u32_f32_e32 v4, v4
	v_mul_lo_u32 v1, v3, v4
	v_mul_hi_u32 v1, v4, v1
	v_add_u32_e32 v1, v4, v1
	v_mul_hi_u32 v1, v5, v1
	v_mul_lo_u32 v3, v1, v2
	v_sub_u32_e32 v3, v5, v3
	v_add_u32_e32 v4, 1, v1
	v_cmp_ge_u32_e32 vcc, v3, v2
	s_nop 1
	v_cndmask_b32_e32 v1, v1, v4, vcc
	v_sub_u32_e32 v4, v3, v2
	v_cndmask_b32_e32 v3, v3, v4, vcc
	v_add_u32_e32 v4, 1, v1
	v_cmp_ge_u32_e32 vcc, v3, v2
	v_add_u32_e32 v3, 1, v5
	s_nop 0
	v_cndmask_b32_e32 v1, v1, v4, vcc
	v_mul_lo_u32 v4, v2, v1
	v_add_u32_e32 v2, v4, v2
	v_cmp_ne_u32_e32 vcc, v3, v2
	s_and_saveexec_b64 s[0:1], vcc
	s_xor_b64 s[8:9], exec, s[0:1]
	s_cbranch_execz .LBB0_1950
	s_waitcnt lgkmcnt(0)
	buffer_inv sc1
	v_mov_b32_e32 v0, 0x3500
	global_load_dword v0, v0, s[86:87] sc1
	s_add_u32 s12, s86, 0x3500
	s_addc_u32 s13, s87, 0
	s_waitcnt vmcnt(0)
	v_cmp_eq_u32_e32 vcc, v0, v1
	s_and_saveexec_b64 s[10:11], vcc
	s_cbranch_execz .LBB0_1949
	s_mov_b32 s22, 1
	s_mov_b64 s[14:15], 0
	v_mov_b32_e32 v0, 0
	s_branch .LBB0_1940
